# attention: 36 divergent mask+bias blocks (LDS read + wait each) replaced by 36 independent LDS reads, then fma + select per element (same fma)
# speedup vs baseline: 1.0559x; 1.0059x over previous
; __device__ void attn_phase(unsigned char* smem, const Params& p, int chunk) {
;     ...
;         f32x4 s[10];
; #pragma unroll
;         for (int kt = 0; kt < 9; ++kt) { s[kt] = (f32x4){0.f, 0.f, 0.f, 0.f};
; #pragma unroll
;             for (int ks = 0; ks < 2; ++ks) { const bf16x8 kfr = *(const bf16x8*)(Ks + (hoff + qs * 16 + kt * 16 + r16) * KST + ks * 32 + g4 * 8); s[kt] = __builtin_amdgcn_mfma_f32_16x16x32_bf16(kfr, qf[ks], s[kt], 0, 0, 0); } }
;         s[9] = (f32x4){0.f, 0.f, 0.f, 0.f};
;         float mx = -1e30f;
; #pragma unroll
;         for (int kt = 0; kt < 9; ++kt)
; #pragma unroll
;             for (int i = 0; i < 4; ++i) { const bool valid = (ub + (unsigned)(16 * kt + i)) <= rng;
;                 const float v = valid ? __builtin_fmaf(s[kt][i], 0.125f * 1.4426950408889634f, bl[16 * kt + i]) : -1e30f; s[kt][i] = v; mx = fmaxf(mx, v); }
.LBB0_76:
	ds_read_b128 v[56:59], v99
	ds_read_b128 v[60:63], v99 offset:64
	ds_read_b128 v[64:67], v99 offset:2304
	ds_read_b128 v[68:71], v99 offset:2368
	ds_read_b128 v[72:75], v99 offset:4608
	s_mul_hi_i32 s31, s24, 0x2aaaaaab
	s_waitcnt lgkmcnt(4)
	v_mfma_f32_16x16x32_bf16 v[56:59], v[56:59], v[52:55], 0
	s_lshr_b32 s34, s31, 31
	s_lshr_b32 s31, s31, 10
	s_add_i32 s31, s31, s34
	s_waitcnt lgkmcnt(3)
	v_mfma_f32_16x16x32_bf16 v[84:87], v[60:63], v[48:51], v[56:59]
	ds_read_b128 v[60:63], v99 offset:6912
	s_mulk_i32 s31, 0x1800
	s_sub_i32 s34, s24, s31
	ds_read_b128 v[56:59], v99 offset:4672
	s_waitcnt lgkmcnt(4)
	v_mfma_f32_16x16x32_bf16 v[64:67], v[64:67], v[52:55], 0
	s_bfe_i32 s35, s34, 0x100004
	s_mulk_i32 s35, 0x2aab
	s_lshr_b32 s36, s35, 31
	s_waitcnt lgkmcnt(3)
	v_mfma_f32_16x16x32_bf16 v[80:83], v[68:71], v[48:51], v[64:67]
	ds_read_b128 v[68:71], v99 offset:6976
	s_lshr_b32 s35, s35, 18
	s_lshl_b32 s24, s34, 1
	s_waitcnt lgkmcnt(3)
	v_mfma_f32_16x16x32_bf16 v[64:67], v[72:75], v[52:55], 0
	ds_read_b128 v[114:117], v99 offset:11584
	s_add_i32 s35, s35, s36
	s_and_b32 s31, s24, 30
	s_waitcnt lgkmcnt(2)
	v_mfma_f32_16x16x32_bf16 v[76:79], v[56:59], v[48:51], v[64:67]
	ds_read_b128 v[56:59], v99 offset:9216
	s_lshr_b32 s24, s34, 4
	s_mul_i32 s35, s35, 24
	ds_read_b128 v[64:67], v99 offset:9280
	v_mfma_f32_16x16x32_bf16 v[60:63], v[60:63], v[52:55], 0
	ds_read_b128 v[118:121], v99 offset:13888
	s_sub_i32 s24, s24, s35
	s_sext_i32_i16 s52, s24
	s_waitcnt lgkmcnt(2)
	v_mfma_f32_16x16x32_bf16 v[56:59], v[56:59], v[52:55], 0
	ds_read_b128 v[122:125], v99 offset:16192
	s_ashr_i32 s24, s52, 2
	s_and_b32 s24, s24, -2
	v_mfma_f32_16x16x32_bf16 v[72:75], v[68:71], v[48:51], v[60:63]
	s_lshr_b32 s35, 32, s24
	s_add_i32 s35, s35, -1
	s_and_b32 s36, s35, s31
	ds_read_b128 v[60:63], v99 offset:11520
	s_waitcnt lgkmcnt(3)
	v_mfma_f32_16x16x32_bf16 v[68:71], v[64:67], v[48:51], v[56:59]
	ds_read_b128 v[126:129], v99 offset:18496
	v_add_u32_e32 v101, s36, v103
	v_not_b32_e32 v113, 63
	ds_read_b128 v[56:59], v99 offset:13824
	s_waitcnt lgkmcnt(2)
	v_mfma_f32_16x16x32_bf16 v[60:63], v[60:63], v[52:55], 0
	v_cmp_eq_u32_e32 vcc, 0, v101
	s_waitcnt lgkmcnt(0)
	v_mfma_f32_16x16x32_bf16 v[56:59], v[56:59], v[52:55], 0
	v_cndmask_b32_e32 v113, v113, v107, vcc
	v_cmp_eq_u32_e32 vcc, s35, v101
	v_mfma_f32_16x16x32_bf16 v[64:67], v[114:117], v[48:51], v[60:63]
	ds_read_b128 v[114:117], v99 offset:16128
	v_mfma_f32_16x16x32_bf16 v[60:63], v[118:121], v[48:51], v[56:59]
	ds_read_b128 v[118:121], v99 offset:18432
	s_waitcnt lgkmcnt(1)
	v_mfma_f32_16x16x32_bf16 v[56:59], v[114:117], v[52:55], 0
	v_cndmask_b32_e32 v114, 64, v108, vcc
	v_sub_u32_e32 v115, v109, v113
	v_sub_u32_e32 v116, v114, v113
	s_waitcnt lgkmcnt(0)
	v_mfma_f32_16x16x32_bf16 v[52:55], v[118:121], v[52:55], 0
	ds_read_b32 v142, v110
	ds_read_b32 v143, v110 offset:4
	ds_read_b32 v144, v110 offset:8
	ds_read_b32 v145, v110 offset:12
	ds_read_b32 v146, v110 offset:64
	ds_read_b32 v147, v110 offset:68
	ds_read_b32 v148, v110 offset:72
	ds_read_b32 v149, v110 offset:76
	ds_read_b32 v150, v110 offset:128
	ds_read_b32 v151, v110 offset:132
	ds_read_b32 v152, v110 offset:136
	ds_read_b32 v153, v110 offset:140
	ds_read_b32 v154, v110 offset:192
	ds_read_b32 v155, v110 offset:196
	ds_read_b32 v156, v110 offset:200
	ds_read_b32 v157, v110 offset:204
	ds_read_b32 v158, v110 offset:256
	ds_read_b32 v159, v110 offset:260
	ds_read_b32 v160, v110 offset:264
	ds_read_b32 v161, v110 offset:268
	ds_read_b32 v162, v110 offset:320
	ds_read_b32 v163, v110 offset:324
	ds_read_b32 v164, v110 offset:328
	ds_read_b32 v165, v110 offset:332
	ds_read_b32 v166, v110 offset:384
	ds_read_b32 v167, v110 offset:388
	ds_read_b32 v168, v110 offset:392
	ds_read_b32 v169, v110 offset:396
	ds_read_b32 v170, v110 offset:448
	ds_read_b32 v171, v110 offset:452
	ds_read_b32 v172, v110 offset:456
	ds_read_b32 v173, v110 offset:460
	ds_read_b32 v174, v110 offset:512
	ds_read_b32 v175, v110 offset:516
	ds_read_b32 v176, v110 offset:520
	ds_read_b32 v177, v110 offset:524
	v_mfma_f32_16x16x32_bf16 v[56:59], v[122:125], v[48:51], v[56:59]
	v_mfma_f32_16x16x32_bf16 v[48:51], v[126:129], v[48:51], v[52:55]
	v_mov_b32_e32 v179, 0xf149f2ca
	s_waitcnt lgkmcnt(0)
; __device__ void attn_phase(unsigned char* smem, const Params& p, int chunk) {
;     ...
;             for (int i = 0; i < 4; ++i) { const bool valid = (ub + (unsigned)(16 * kt + i)) <= rng;
;                 const float v = valid ? __builtin_fmaf(s[kt][i], 0.125f * 1.4426950408889634f, bl[16 * kt + i]) : -1e30f; s[kt][i] = v; mx = fmaxf(mx, v); }
;         mx = fmaxf(mx, __shfl_xor(mx, 16)); mx = fmaxf(mx, __shfl_xor(mx, 32));
	v_cmp_le_u32_e32 vcc, v115, v116
	v_fmac_f32_e32 v142, 0x3e38aa3b, v84
	s_nop 0
	v_cndmask_b32_e32 v114, v179, v142, vcc
	v_add_u32_e32 v178, 1, v115
	v_cmp_le_u32_e32 vcc, v178, v116
	v_fmac_f32_e32 v143, 0x3e38aa3b, v85
	s_nop 0
	v_cndmask_b32_e32 v113, v179, v143, vcc
	v_add_u32_e32 v178, 2, v115
	v_cmp_le_u32_e32 vcc, v178, v116
	v_fmac_f32_e32 v144, 0x3e38aa3b, v86
	s_nop 0
	v_cndmask_b32_e32 v85, v179, v144, vcc
	v_add_u32_e32 v178, 3, v115
	v_cmp_le_u32_e32 vcc, v178, v116
	v_fmac_f32_e32 v145, 0x3e38aa3b, v87
	s_nop 0
	v_cndmask_b32_e32 v84, v179, v145, vcc
	v_add_u32_e32 v178, 16, v115
	v_cmp_le_u32_e32 vcc, v178, v116
	v_fmac_f32_e32 v146, 0x3e38aa3b, v80
	s_nop 0
	v_cndmask_b32_e32 v87, v179, v146, vcc
	v_add_u32_e32 v178, 17, v115
	v_cmp_le_u32_e32 vcc, v178, v116
	v_fmac_f32_e32 v147, 0x3e38aa3b, v81
	s_nop 0
	v_cndmask_b32_e32 v86, v179, v147, vcc
	v_add_u32_e32 v178, 18, v115
	v_cmp_le_u32_e32 vcc, v178, v116
	v_fmac_f32_e32 v148, 0x3e38aa3b, v82
	s_nop 0
	v_cndmask_b32_e32 v81, v179, v148, vcc
	v_add_u32_e32 v178, 19, v115
	v_cmp_le_u32_e32 vcc, v178, v116
	v_fmac_f32_e32 v149, 0x3e38aa3b, v83
	s_nop 0
	v_cndmask_b32_e32 v80, v179, v149, vcc
	v_add_u32_e32 v178, 32, v115
	v_cmp_le_u32_e32 vcc, v178, v116
	v_fmac_f32_e32 v150, 0x3e38aa3b, v76
	s_nop 0
	v_cndmask_b32_e32 v83, v179, v150, vcc
	v_add_u32_e32 v178, 33, v115
	v_cmp_le_u32_e32 vcc, v178, v116
	v_fmac_f32_e32 v151, 0x3e38aa3b, v77
	s_nop 0
	v_cndmask_b32_e32 v82, v179, v151, vcc
	v_add_u32_e32 v178, 34, v115
	v_cmp_le_u32_e32 vcc, v178, v116
	v_fmac_f32_e32 v152, 0x3e38aa3b, v78
	s_nop 0
	v_cndmask_b32_e32 v77, v179, v152, vcc
	v_add_u32_e32 v178, 35, v115
	v_cmp_le_u32_e32 vcc, v178, v116
	v_fmac_f32_e32 v153, 0x3e38aa3b, v79
	s_nop 0
	v_cndmask_b32_e32 v76, v179, v153, vcc
	v_add_u32_e32 v178, 48, v115
	v_cmp_le_u32_e32 vcc, v178, v116
	v_fmac_f32_e32 v154, 0x3e38aa3b, v72
	s_nop 0
	v_cndmask_b32_e32 v79, v179, v154, vcc
	v_add_u32_e32 v178, 49, v115
	v_cmp_le_u32_e32 vcc, v178, v116
	v_fmac_f32_e32 v155, 0x3e38aa3b, v73
	s_nop 0
	v_cndmask_b32_e32 v78, v179, v155, vcc
	v_add_u32_e32 v178, 50, v115
	v_cmp_le_u32_e32 vcc, v178, v116
	v_fmac_f32_e32 v156, 0x3e38aa3b, v74
	s_nop 0
	v_cndmask_b32_e32 v73, v179, v156, vcc
	v_add_u32_e32 v178, 51, v115
	v_cmp_le_u32_e32 vcc, v178, v116
	v_fmac_f32_e32 v157, 0x3e38aa3b, v75
	s_nop 0
	v_cndmask_b32_e32 v72, v179, v157, vcc
	v_add_u32_e32 v178, 64, v115
	v_cmp_le_u32_e32 vcc, v178, v116
	v_fmac_f32_e32 v158, 0x3e38aa3b, v68
	s_nop 0
	v_cndmask_b32_e32 v75, v179, v158, vcc
	v_add_u32_e32 v178, 0x41, v115
	v_cmp_le_u32_e32 vcc, v178, v116
	v_fmac_f32_e32 v159, 0x3e38aa3b, v69
	s_nop 0
	v_cndmask_b32_e32 v74, v179, v159, vcc
	v_add_u32_e32 v178, 0x42, v115
	v_cmp_le_u32_e32 vcc, v178, v116
	v_fmac_f32_e32 v160, 0x3e38aa3b, v70
	s_nop 0
	v_cndmask_b32_e32 v69, v179, v160, vcc
	v_add_u32_e32 v178, 0x43, v115
	v_cmp_le_u32_e32 vcc, v178, v116
	v_fmac_f32_e32 v161, 0x3e38aa3b, v71
	s_nop 0
	v_cndmask_b32_e32 v68, v179, v161, vcc
	v_add_u32_e32 v178, 0x50, v115
	v_cmp_le_u32_e32 vcc, v178, v116
	v_fmac_f32_e32 v162, 0x3e38aa3b, v64
	s_nop 0
	v_cndmask_b32_e32 v71, v179, v162, vcc
	v_add_u32_e32 v178, 0x51, v115
	v_cmp_le_u32_e32 vcc, v178, v116
	v_fmac_f32_e32 v163, 0x3e38aa3b, v65
	s_nop 0
	v_cndmask_b32_e32 v70, v179, v163, vcc
	v_add_u32_e32 v178, 0x52, v115
	v_cmp_le_u32_e32 vcc, v178, v116
	v_fmac_f32_e32 v164, 0x3e38aa3b, v66
	s_nop 0
	v_cndmask_b32_e32 v118, v179, v164, vcc
	v_add_u32_e32 v178, 0x53, v115
	v_cmp_le_u32_e32 vcc, v178, v116
	v_fmac_f32_e32 v165, 0x3e38aa3b, v67
	s_nop 0
	v_cndmask_b32_e32 v117, v179, v165, vcc
	v_add_u32_e32 v178, 0x60, v115
	v_cmp_le_u32_e32 vcc, v178, v116
	v_fmac_f32_e32 v166, 0x3e38aa3b, v60
	s_nop 0
	v_cndmask_b32_e32 v65, v179, v166, vcc
	v_add_u32_e32 v178, 0x61, v115
	v_cmp_le_u32_e32 vcc, v178, v116
	v_fmac_f32_e32 v167, 0x3e38aa3b, v61
	s_nop 0
	v_cndmask_b32_e32 v64, v179, v167, vcc
	v_add_u32_e32 v178, 0x62, v115
	v_cmp_le_u32_e32 vcc, v178, v116
	v_fmac_f32_e32 v168, 0x3e38aa3b, v62
	s_nop 0
	v_cndmask_b32_e32 v66, v179, v168, vcc
	v_add_u32_e32 v178, 0x63, v115
	v_cmp_le_u32_e32 vcc, v178, v116
	v_fmac_f32_e32 v169, 0x3e38aa3b, v63
	s_nop 0
	v_cndmask_b32_e32 v60, v179, v169, vcc
	v_add_u32_e32 v178, 0x70, v115
	v_cmp_le_u32_e32 vcc, v178, v116
	v_fmac_f32_e32 v170, 0x3e38aa3b, v56
	s_nop 0
	v_cndmask_b32_e32 v62, v179, v170, vcc
	v_add_u32_e32 v178, 0x71, v115
	v_cmp_le_u32_e32 vcc, v178, v116
	v_fmac_f32_e32 v171, 0x3e38aa3b, v57
	s_nop 0
	v_cndmask_b32_e32 v61, v179, v171, vcc
	v_add_u32_e32 v178, 0x72, v115
	v_cmp_le_u32_e32 vcc, v178, v116
	v_fmac_f32_e32 v172, 0x3e38aa3b, v58
	s_nop 0
	v_cndmask_b32_e32 v55, v179, v172, vcc
	v_add_u32_e32 v178, 0x73, v115
	v_cmp_le_u32_e32 vcc, v178, v116
	v_fmac_f32_e32 v173, 0x3e38aa3b, v59
	s_nop 0
	v_cndmask_b32_e32 v54, v179, v173, vcc
	v_add_u32_e32 v178, 0x80, v115
	v_cmp_le_u32_e32 vcc, v178, v116
	v_fmac_f32_e32 v174, 0x3e38aa3b, v48
	s_nop 0
	v_cndmask_b32_e32 v56, v179, v174, vcc
	v_add_u32_e32 v178, 0x81, v115
	v_cmp_le_u32_e32 vcc, v178, v116
	v_fmac_f32_e32 v175, 0x3e38aa3b, v49
	s_nop 0
	v_cndmask_b32_e32 v52, v179, v175, vcc
	v_add_u32_e32 v178, 0x82, v115
	v_cmp_le_u32_e32 vcc, v178, v116
	v_fmac_f32_e32 v176, 0x3e38aa3b, v50
	s_nop 0
	v_cndmask_b32_e32 v53, v179, v176, vcc
	v_add_u32_e32 v178, 0x83, v115
	v_cmp_le_u32_e32 vcc, v178, v116
	v_fmac_f32_e32 v177, 0x3e38aa3b, v51
	s_nop 0
	v_cndmask_b32_e32 v49, v179, v177, vcc
	s_mov_b32 s35, 0xf149f2ca
	v_max3_f32 v48, v114, s35, v113
	v_max3_f32 v48, v48, v85, v84
	v_max3_f32 v48, v48, v87, v86
	v_max3_f32 v48, v48, v81, v80
	v_max3_f32 v48, v48, v83, v82
	v_max3_f32 v48, v48, v77, v76
	v_max3_f32 v48, v48, v79, v78
	v_max3_f32 v48, v48, v73, v72
	v_max3_f32 v48, v48, v75, v74
	v_max3_f32 v48, v48, v69, v68
	v_max3_f32 v48, v48, v71, v70
	v_max3_f32 v48, v48, v118, v117
	v_max3_f32 v48, v48, v65, v64
	v_max3_f32 v48, v48, v66, v60
	v_max3_f32 v48, v48, v62, v61
	v_max3_f32 v48, v48, v55, v54
	v_max3_f32 v48, v48, v56, v52
	v_and_b32_e32 v51, 64, v243
	v_max3_f32 v50, v48, v53, v49
	v_xor_b32_e32 v48, 16, v243
	v_add_u32_e32 v51, 64, v51
	v_cmp_lt_i32_e32 vcc, v48, v51
	s_mulk_i32 s34, 0x2aab
	s_lshr_b32 s35, s34, 31
	v_cndmask_b32_e32 v48, v243, v48, vcc
	v_lshlrev_b32_e32 v48, 2, v48
	ds_bpermute_b32 v57, v48, v50
	s_ashr_i32 s34, s34, 22
	s_add_i32 s34, s34, s35
	s_sub_i32 s35, 5, s24
	s_bfe_i64 s[58:59], s[34:35], 0x100000
	s_waitcnt lgkmcnt(0)
; #define LAS __attribute__((address_space(3)))
; __device__ __forceinline__ unsigned cvt_pk_bf16(float lo, float hi) { const f32x2_t v = {lo, hi}; const bf16x2_t b = __builtin_convertvector(v, bf16x2_t); return __builtin_bit_cast(unsigned, b); }
; __device__ void attn_phase(unsigned char* smem, const Params& p, int chunk) {
;     ...
;         float den = 0.f;
; #pragma unroll
;         for (int kt = 0; kt < 9; ++kt)
; #pragma unroll
;             for (int i = 0; i < 4; ++i) { const float e = __builtin_amdgcn_exp2f(s[kt][i] - mx); s[kt][i] = e; den += e; }
;         den += __shfl_xor(den, 16); den += __shfl_xor(den, 32);
;         f32x4 o[4];
; #pragma unroll
;         for (int et = 0; et < 4; ++et) o[et] = (f32x4){0.f, 0.f, 0.f, 0.f};
;         const bf16_t* vbase = Vs + (hoff + qs * 16 + 4 * g4 + (r16 >> 2)) * VSR + 4 * (r16 & 3);
; #pragma unroll
;         for (int cc = 0; cc < 5; ++cc) {
;             union { u32x4 u; bf16x8 v; } pf; pf.u.x = cvt_pk_bf16(s[2 * cc][0], s[2 * cc][1]); pf.u.y = cvt_pk_bf16(s[2 * cc][2], s[2 * cc][3]);
;             pf.u.z = cvt_pk_bf16(s[2 * cc + 1][0], s[2 * cc + 1][1]); pf.u.w = cvt_pk_bf16(s[2 * cc + 1][2], s[2 * cc + 1][3]);
; #pragma unroll
;             for (int et = 0; et < 4; ++et) { const bf16_t* vp = vbase + (cc * 32) * VSR + et * 16;
;                 const s16x4 v0 = __builtin_amdgcn_ds_read_tr16_b64_v4i16((LAS s16x4*)(LAS unsigned char*)vp), v1 = __builtin_amdgcn_ds_read_tr16_b64_v4i16((LAS s16x4*)(LAS unsigned char*)(vp + 16 * VSR));
;                 const bf16x8 vf = {v0[0], v0[1], v0[2], v0[3], v1[0], v1[1], v1[2], v1[3]};
;                 o[et] = __builtin_amdgcn_mfma_f32_16x16x32_bf16(vf, pf.v, o[et], 0, 0, 0); } }
	v_max_f32_e32 v57, v57, v57
	v_max_f32_e32 v50, v50, v57
	v_xor_b32_e32 v57, 32, v243
	v_cmp_lt_i32_e32 vcc, v57, v51
	s_lshr_b32 s31, s31, s35
	s_lshl_b64 s[34:35], s[58:59], 11
	v_cndmask_b32_e32 v51, v243, v57, vcc
	v_lshlrev_b32_e32 v51, 2, v51
	ds_bpermute_b32 v57, v51, v50
	s_or_b32 s34, s34, s31
	s_waitcnt lgkmcnt(0)
	v_max_f32_e32 v57, v57, v57
	v_max_f32_e32 v50, v50, v57
	v_sub_f32_e32 v57, v114, v50
	v_exp_f32_e32 v57, v57
	v_sub_f32_e32 v58, v113, v50
	v_exp_f32_e32 v58, v58
	v_sub_f32_e32 v59, v85, v50
	v_exp_f32_e32 v59, v59
	v_sub_f32_e32 v63, v84, v50
	v_exp_f32_e32 v63, v63
	v_sub_f32_e32 v84, v87, v50
	v_add_f32_e32 v67, 0, v57
	v_exp_f32_e32 v84, v84
	v_sub_f32_e32 v85, v86, v50
	v_add_f32_e32 v67, v58, v67
	v_exp_f32_e32 v85, v85
	v_sub_f32_e32 v81, v81, v50
	v_add_f32_e32 v67, v59, v67
	v_exp_f32_e32 v81, v81
	v_sub_f32_e32 v80, v80, v50
	v_add_f32_e32 v67, v63, v67
	v_exp_f32_e32 v80, v80
	v_sub_f32_e32 v83, v83, v50
	v_add_f32_e32 v67, v84, v67
	v_exp_f32_e32 v113, v83
	v_sub_f32_e32 v82, v82, v50
	v_add_f32_e32 v67, v85, v67
	v_exp_f32_e32 v114, v82
	v_sub_f32_e32 v77, v77, v50
	v_add_f32_e32 v67, v81, v67
	v_exp_f32_e32 v115, v77
	v_sub_f32_e32 v76, v76, v50
	v_add_f32_e32 v67, v80, v67
	v_exp_f32_e32 v116, v76
	v_sub_f32_e32 v76, v79, v50
	v_add_f32_e32 v67, v113, v67
	v_exp_f32_e32 v119, v76
	v_sub_f32_e32 v76, v78, v50
	v_add_f32_e32 v67, v114, v67
	v_exp_f32_e32 v120, v76
	v_sub_f32_e32 v73, v73, v50
	v_add_f32_e32 v67, v115, v67
	v_exp_f32_e32 v121, v73
	v_sub_f32_e32 v72, v72, v50
	v_add_f32_e32 v67, v116, v67
	v_exp_f32_e32 v122, v72
	v_sub_f32_e32 v72, v75, v50
	v_add_f32_e32 v67, v119, v67
	v_exp_f32_e32 v126, v72
	v_sub_f32_e32 v72, v74, v50
	v_add_f32_e32 v67, v120, v67
	v_exp_f32_e32 v127, v72
	v_sub_f32_e32 v69, v69, v50
	v_add_f32_e32 v67, v121, v67
	v_exp_f32_e32 v128, v69
	v_sub_f32_e32 v68, v68, v50
	v_add_f32_e32 v67, v122, v67
	v_exp_f32_e32 v129, v68
	v_sub_f32_e32 v68, v71, v50
	v_add_f32_e32 v67, v126, v67
	v_exp_f32_e32 v130, v68
	v_sub_f32_e32 v68, v70, v50
	v_add_f32_e32 v67, v127, v67
	v_exp_f32_e32 v131, v68
	v_sub_f32_e32 v68, v118, v50
	v_add_f32_e32 v67, v128, v67
	v_exp_f32_e32 v132, v68
	v_sub_f32_e32 v68, v117, v50
	v_add_f32_e32 v67, v129, v67
	v_exp_f32_e32 v133, v68
	v_cvt_pk_bf16_f32 v68, v57, v58
	ds_read_b64_tr_b16 v[74:75], v111 offset:41472
	ds_read_b64_tr_b16 v[72:73], v111 offset:39168
	v_cvt_pk_bf16_f32 v70, v84, v85
	v_cvt_pk_bf16_f32 v71, v81, v80
	ds_read_b64_tr_b16 v[78:79], v111 offset:41504
	ds_read_b64_tr_b16 v[76:77], v111 offset:39200
	ds_read_b64_tr_b16 v[80:81], v111 offset:39232
	ds_read_b64_tr_b16 v[84:85], v111 offset:39264
	ds_read_b64_tr_b16 v[82:83], v111 offset:41536
	ds_read_b64_tr_b16 v[86:87], v111 offset:41568
	v_sub_f32_e32 v57, v65, v50
	v_add_f32_e32 v67, v130, v67
	v_exp_f32_e32 v134, v57
	v_add_f32_e32 v67, v131, v67
	v_add_f32_e32 v67, v132, v67
	v_sub_f32_e32 v57, v64, v50
	v_add_f32_e32 v117, v133, v67
	v_cvt_pk_bf16_f32 v69, v59, v63
	v_exp_f32_e32 v135, v57
	v_sub_f32_e32 v57, v66, v50
	s_waitcnt lgkmcnt(6)
	v_mfma_f32_16x16x32_bf16 v[72:75], v[72:75], v[68:71], 0
	v_exp_f32_e32 v136, v57
	v_add_f32_e32 v57, v134, v117
	v_sub_f32_e32 v58, v60, v50
	s_waitcnt lgkmcnt(4)
	v_mfma_f32_16x16x32_bf16 v[76:79], v[76:79], v[68:71], 0
	v_add_f32_e32 v57, v135, v57
	v_sub_f32_e32 v55, v55, v50
	v_add_f32_e32 v57, v136, v57
	s_waitcnt lgkmcnt(1)
	v_mfma_f32_16x16x32_bf16 v[64:67], v[80:83], v[68:71], 0
	v_cvt_pk_bf16_f32 v80, v113, v114
	v_cvt_pk_bf16_f32 v81, v115, v116
	v_cvt_pk_bf16_f32 v82, v119, v120
	s_waitcnt lgkmcnt(0)
	v_mfma_f32_16x16x32_bf16 v[68:71], v[84:87], v[68:71], 0
	ds_read_b64_tr_b16 v[84:85], v111 offset:43776
	ds_read_b64_tr_b16 v[86:87], v111 offset:46080
	v_cvt_pk_bf16_f32 v83, v121, v122
	ds_read_b64_tr_b16 v[116:117], v111 offset:46112
	ds_read_b64_tr_b16 v[114:115], v111 offset:43808
	ds_read_b64_tr_b16 v[118:119], v111 offset:43840
	ds_read_b64_tr_b16 v[122:123], v111 offset:43872
	ds_read_b64_tr_b16 v[120:121], v111 offset:46144
	ds_read_b64_tr_b16 v[124:125], v111 offset:46176
	v_exp_f32_e32 v113, v58
	v_sub_f32_e32 v58, v62, v50
	v_exp_f32_e32 v137, v58
	v_sub_f32_e32 v58, v61, v50
	s_waitcnt lgkmcnt(6)
	v_mfma_f32_16x16x32_bf16 v[72:75], v[84:87], v[80:83], v[72:75]
	v_exp_f32_e32 v138, v58
	v_sub_f32_e32 v54, v54, v50
	v_add_f32_e32 v57, v113, v57
	s_waitcnt lgkmcnt(4)
	v_mfma_f32_16x16x32_bf16 v[76:79], v[114:117], v[80:83], v[76:79]
	v_add_f32_e32 v57, v137, v57
	v_add_f32_e32 v139, v138, v57
	v_sub_f32_e32 v52, v52, v50
	s_waitcnt lgkmcnt(1)
	v_mfma_f32_16x16x32_bf16 v[58:61], v[118:121], v[80:83], v[64:67]
	v_sub_f32_e32 v49, v49, v50
	v_exp_f32_e32 v49, v49
	s_waitcnt lgkmcnt(0)
	v_mfma_f32_16x16x32_bf16 v[62:65], v[122:125], v[80:83], v[68:71]
	ds_read_b64_tr_b16 v[80:81], v111 offset:48384
	ds_read_b64_tr_b16 v[82:83], v111 offset:50688
	v_cvt_pk_bf16_f32 v66, v126, v127
	v_cvt_pk_bf16_f32 v67, v128, v129
	v_cvt_pk_bf16_f32 v68, v130, v131
	v_cvt_pk_bf16_f32 v69, v132, v133
	ds_read_b64_tr_b16 v[86:87], v111 offset:50720
	ds_read_b64_tr_b16 v[84:85], v111 offset:48416
	ds_read_b64_tr_b16 v[114:115], v111 offset:48448
	ds_read_b64_tr_b16 v[118:119], v111 offset:48480
	ds_read_b64_tr_b16 v[116:117], v111 offset:50752
	ds_read_b64_tr_b16 v[120:121], v111 offset:50784
	s_waitcnt lgkmcnt(6)
; #define LAS __attribute__((address_space(3)))
; __device__ __forceinline__ unsigned cvt_pk_bf16(float lo, float hi) { const f32x2_t v = {lo, hi}; const bf16x2_t b = __builtin_convertvector(v, bf16x2_t); return __builtin_bit_cast(unsigned, b); }
; __device__ void attn_phase(unsigned char* smem, const Params& p, int chunk) {
;     ...
;         for (int cc = 0; cc < 5; ++cc) {
;             union { u32x4 u; bf16x8 v; } pf; pf.u.x = cvt_pk_bf16(s[2 * cc][0], s[2 * cc][1]); pf.u.y = cvt_pk_bf16(s[2 * cc][2], s[2 * cc][3]);
;             pf.u.z = cvt_pk_bf16(s[2 * cc + 1][0], s[2 * cc + 1][1]); pf.u.w = cvt_pk_bf16(s[2 * cc + 1][2], s[2 * cc + 1][3]);
; #pragma unroll
;             for (int et = 0; et < 4; ++et) { const bf16_t* vp = vbase + (cc * 32) * VSR + et * 16;
;                 const s16x4 v0 = __builtin_amdgcn_ds_read_tr16_b64_v4i16((LAS s16x4*)(LAS unsigned char*)vp), v1 = __builtin_amdgcn_ds_read_tr16_b64_v4i16((LAS s16x4*)(LAS unsigned char*)(vp + 16 * VSR));
;                 const bf16x8 vf = {v0[0], v0[1], v0[2], v0[3], v1[0], v1[1], v1[2], v1[3]};
;                 o[et] = __builtin_amdgcn_mfma_f32_16x16x32_bf16(vf, pf.v, o[et], 0, 0, 0); } }
;         const float inv = __builtin_amdgcn_rcpf(den);
;         bf16_t* op = qkv + qtok * QKVC + hh * 64 + 4 * g4;
; #pragma unroll
;         for (int et = 0; et < 4; ++et) { u32x2 wv; wv.x = cvt_pk_bf16(o[et][0] * inv, o[et][1] * inv); wv.y = cvt_pk_bf16(o[et][2] * inv, o[et][3] * inv); *(u32x2*)(op + et * 16) = wv; }
;         if (g4 == 0) lse[qtok * 24 + hh] = mx * 0.6931471805599453f + logf(den);
	v_mfma_f32_16x16x32_bf16 v[70:73], v[80:83], v[66:69], v[72:75]
	v_exp_f32_e32 v80, v55
	s_waitcnt lgkmcnt(4)
	v_mfma_f32_16x16x32_bf16 v[74:77], v[84:87], v[66:69], v[76:79]
	s_nop 2
	v_exp_f32_e32 v78, v54
	v_sub_f32_e32 v54, v56, v50
	v_exp_f32_e32 v86, v54
	s_waitcnt lgkmcnt(1)
	v_mfma_f32_16x16x32_bf16 v[54:57], v[114:117], v[66:69], v[58:61]
	s_nop 2
	v_add_f32_e32 v58, v80, v139
	v_add_f32_e32 v58, v78, v58
	v_add_f32_e32 v87, v86, v58
	s_waitcnt lgkmcnt(0)
	v_mfma_f32_16x16x32_bf16 v[58:61], v[118:121], v[66:69], v[62:65]
	ds_read_b64_tr_b16 v[66:67], v111 offset:52992
	ds_read_b64_tr_b16 v[68:69], v111 offset:55296
	s_nop 0
	v_cvt_pk_bf16_f32 v62, v134, v135
	v_cvt_pk_bf16_f32 v63, v136, v113
	v_cvt_pk_bf16_f32 v64, v137, v138
	v_cvt_pk_bf16_f32 v65, v80, v78
	ds_read_b64_tr_b16 v[80:81], v111 offset:55328
	ds_read_b64_tr_b16 v[78:79], v111 offset:53024
	ds_read_b64_tr_b16 v[82:83], v111 offset:53056
	ds_read_b64_tr_b16 v[114:115], v111 offset:53088
	ds_read_b64_tr_b16 v[84:85], v111 offset:55360
	ds_read_b64_tr_b16 v[116:117], v111 offset:55392
	v_exp_f32_e32 v113, v52
	v_sub_f32_e32 v52, v53, v50
	s_waitcnt lgkmcnt(6)
	v_mfma_f32_16x16x32_bf16 v[66:69], v[66:69], v[62:65], v[70:73]
	s_waitcnt lgkmcnt(4)
	v_mfma_f32_16x16x32_bf16 v[70:73], v[78:81], v[62:65], v[74:77]
	s_nop 2
	v_exp_f32_e32 v74, v52
	s_waitcnt lgkmcnt(1)
	v_mfma_f32_16x16x32_bf16 v[52:55], v[82:85], v[62:65], v[54:57]
	s_nop 2
	v_add_f32_e32 v56, v113, v87
	v_add_f32_e32 v56, v74, v56
	v_add_f32_e32 v87, v49, v56
	s_waitcnt lgkmcnt(0)
	v_mfma_f32_16x16x32_bf16 v[56:59], v[114:117], v[62:65], v[58:61]
	v_mov_b32_e32 v62, v185
	v_mov_b32_e32 v63, v185
	s_nop 0
	v_cvt_pk_bf16_f32 v61, v74, v49
	ds_read_b64_tr_b16 v[74:75], v111 offset:57600
	ds_read_b64_tr_b16 v[76:77], v111 offset:59904
	ds_bpermute_b32 v49, v48, v87
	v_cvt_pk_bf16_f32 v60, v86, v113
	ds_read_b64_tr_b16 v[80:81], v111 offset:59936
	ds_read_b64_tr_b16 v[78:79], v111 offset:57632
	ds_read_b64_tr_b16 v[82:83], v111 offset:57664
	ds_read_b64_tr_b16 v[114:115], v111 offset:57696
	ds_read_b64_tr_b16 v[84:85], v111 offset:59968
	ds_read_b64_tr_b16 v[116:117], v111 offset:60000
	s_waitcnt lgkmcnt(7)
	v_mfma_f32_16x16x32_bf16 v[64:67], v[74:77], v[60:63], v[66:69]
	v_lshl_or_b32 v48, v101, 6, v106
	v_mov_b32_e32 v101, v185
	s_waitcnt lgkmcnt(4)
	v_mfma_f32_16x16x32_bf16 v[68:71], v[78:81], v[60:63], v[70:73]
	s_nop 2
	v_add_f32_e32 v72, v87, v49
	ds_bpermute_b32 v51, v51, v72
	v_ashrrev_i32_e32 v49, 31, v48
	v_lshlrev_b64 v[48:49], s24, v[48:49]
	s_waitcnt lgkmcnt(2)
	v_mfma_f32_16x16x32_bf16 v[52:55], v[82:85], v[60:63], v[52:55]
	v_lshl_add_u64 v[48:49], s[34:35], 0, v[48:49]
	s_waitcnt lgkmcnt(0)
	v_add_f32_e32 v51, v72, v51
	v_mfma_f32_16x16x32_bf16 v[56:59], v[114:117], v[60:63], v[56:59]
	v_mov_b64_e32 v[62:63], s[6:7]
	v_mad_u64_u32 v[62:63], s[34:35], v48, s93, v[62:63]
	v_rcp_f32_e32 v60, v51
	v_mov_b32_e32 v72, v63
	v_mad_u64_u32 v[72:73], s[34:35], v49, s93, v[72:73]
	s_lshl_b32 s34, s52, 6
	v_mov_b32_e32 v63, v72
	s_ashr_i32 s35, s34, 31
	v_lshl_add_u64 v[62:63], s[34:35], 1, v[62:63]
	v_pk_mul_f32 v[64:65], v[60:61], v[64:65] op_sel_hi:[0,1]
	v_pk_mul_f32 v[66:67], v[60:61], v[66:67] op_sel_hi:[0,1]
	v_pk_mul_f32 v[52:53], v[60:61], v[52:53] op_sel_hi:[0,1]
	v_pk_mul_f32 v[54:55], v[60:61], v[54:55] op_sel_hi:[0,1]
	v_lshl_add_u64 v[62:63], v[62:63], 0, v[100:101]
	v_cvt_pk_bf16_f32 v64, v64, v65
	v_cvt_pk_bf16_f32 v65, v66, v67
	v_cvt_pk_bf16_f32 v52, v52, v53
	v_cvt_pk_bf16_f32 v53, v54, v55
	global_store_dwordx2 v[62:63], v[64:65], off
	v_pk_mul_f32 v[64:65], v[60:61], v[68:69] op_sel_hi:[0,1]
	v_pk_mul_f32 v[66:67], v[60:61], v[70:71] op_sel_hi:[0,1]
	global_store_dwordx2 v[62:63], v[52:53], off offset:64
	v_pk_mul_f32 v[52:53], v[60:61], v[56:57] op_sel_hi:[0,1]
	v_pk_mul_f32 v[54:55], v[60:61], v[58:59] op_sel_hi:[0,1]
	v_cvt_pk_bf16_f32 v64, v64, v65
	v_cvt_pk_bf16_f32 v65, v66, v67
	v_cvt_pk_bf16_f32 v52, v52, v53
	v_cvt_pk_bf16_f32 v53, v54, v55
	global_store_dwordx2 v[62:63], v[64:65], off offset:32
	global_store_dwordx2 v[62:63], v[52:53], off offset:96
	s_and_saveexec_b64 s[58:59], s[10:11]
	s_cbranch_execz .LBB0_49
	s_mov_b32 s24, 0x800000
	v_cmp_gt_f32_e32 vcc, s24, v51
	s_mov_b32 s24, 0x3f317217
	s_ashr_i32 s53, s52, 31
	v_cndmask_b32_e64 v52, 0, 32, vcc
	v_ldexp_f32 v51, v51, v52
	v_log_f32_e32 v51, v51
	v_cndmask_b32_e32 v52, 0, v140, vcc
	v_mul_f32_e32 v53, 0x3f317217, v51
	v_fma_f32 v53, v51, s24, -v53
	v_fmac_f32_e32 v53, 0x3377d1cf, v51
	v_fmac_f32_e32 v53, 0x3f317217, v51
	v_cmp_lt_f32_e64 vcc, |v51|, s70
	s_nop 1
	v_cndmask_b32_e32 v51, v51, v53, vcc
	v_sub_f32_e32 v52, v51, v52
	v_fmac_f32_e32 v52, 0x3f317218, v50
	v_mov_b64_e32 v[50:51], s[0:1]
	v_mad_u64_u32 v[50:51], s[34:35], v48, s92, v[50:51]
	v_mov_b32_e32 v48, v51
	v_mad_u64_u32 v[48:49], s[34:35], v49, s92, v[48:49]
	v_mov_b32_e32 v51, v48
	v_lshl_add_u64 v[48:49], s[52:53], 2, v[50:51]
	global_store_dword v[48:49], v52, off
	s_branch .LBB0_49
